# P0 GEMV cross-lane reductions batched by level (108 serialized ds_bpermute round trips -> 9) and final cross-wave reduction loads issued together
# speedup vs baseline: 1.0168x; 1.0012x over previous
.LBB0_417:
	s_mov_b32 s5, 0xfeb00000
	v_add_co_u32_e64 v2, s[42:43], s5, v20
	s_mov_b32 s5, 0xfee00000
	s_nop 0
	v_addc_co_u32_e64 v3, s[42:43], -1, v21, s[42:43]
	v_add_co_u32_e64 v4, s[42:43], s5, v20
	s_mov_b32 s5, 0xff100000
	s_nop 0
	v_addc_co_u32_e64 v5, s[42:43], -1, v21, s[42:43]
	v_add_co_u32_e64 v6, s[42:43], s5, v20
	s_mov_b32 s5, 0xff400000
	s_nop 0
	v_addc_co_u32_e64 v7, s[42:43], -1, v21, s[42:43]
	v_add_co_u32_e64 v8, s[42:43], s5, v20
	s_mov_b32 s5, 0xff700000
	s_nop 0
	v_addc_co_u32_e64 v9, s[42:43], -1, v21, s[42:43]
	v_add_co_u32_e64 v10, s[42:43], s5, v20
	s_mov_b32 s5, 0xffa00000
	s_nop 0
	v_addc_co_u32_e64 v11, s[42:43], -1, v21, s[42:43]
	v_add_co_u32_e64 v12, s[42:43], s5, v20
	s_mov_b32 s5, 0xffd00000
	s_nop 0
	v_addc_co_u32_e64 v13, s[42:43], -1, v21, s[42:43]
	v_add_co_u32_e64 v46, s[42:43], s5, v20
	v_add_u32_e32 v65, s4, v17
	s_nop 0
	v_addc_co_u32_e64 v47, s[42:43], -1, v21, s[42:43]
	global_load_dwordx4 v[60:63], v[2:3], off
	global_load_dwordx4 v[78:81], v[4:5], off
	global_load_dwordx4 v[82:85], v[6:7], off
	global_load_dwordx4 v[86:89], v[8:9], off
	global_load_dwordx4 v[90:93], v[10:11], off
	s_nop 0
	global_load_dwordx4 v[10:13], v[12:13], off
	s_nop 0
	global_load_dwordx4 v[6:9], v[46:47], off
	global_load_dwordx4 v[2:5], v[20:21], off
	v_add_u32_e32 v0, 0x10000, v65
	v_add_u32_e32 v22, 0x10100, v65
	v_add_u32_e32 v47, 0x10200, v65
	v_add_u32_e32 v48, 0x10300, v65
	v_add_u32_e32 v49, 0x10400, v65
	v_add_u32_e32 v50, 0x10500, v65
	v_add_u32_e32 v51, 0x10600, v65
	v_add_u32_e32 v71, 0x10700, v65
	ds_read_b32 v46, v0
	ds_read_b32 v64, v22
	ds_read_b32 v70, v47
	ds_read_b32 v74, v48
	ds_read_b32 v94, v49
	ds_read_b32 v52, v50
	ds_read_b32 v22, v51
	ds_read_b32 v0, v71
	ds_read2st64_b32 v[100:101], v65 offset1:1
	ds_read2st64_b32 v[102:103], v65 offset0:2 offset1:3
	ds_read2st64_b32 v[104:105], v65 offset0:4 offset1:5
	ds_read2st64_b32 v[50:51], v65 offset0:6 offset1:7
	ds_read2st64_b32 v[106:107], v65 offset0:32 offset1:33
	ds_read2st64_b32 v[108:109], v65 offset0:34 offset1:35
	ds_read2st64_b32 v[110:111], v65 offset0:36 offset1:37
	ds_read2st64_b32 v[48:49], v65 offset0:38 offset1:39
	s_addk_i32 s4, 0x800
	s_mov_b64 s[8:9], 0x1800000
	v_lshl_add_u64 v[20:21], v[20:21], 0, s[8:9]
	s_cmpk_eq_i32 s4, 0x2000
	s_waitcnt vmcnt(7) lgkmcnt(14)
	v_pk_fma_f32 v[96:97], v[60:61], v[46:47], v[26:27] op_sel_hi:[1,0,1]
	v_pk_fma_f32 v[98:99], v[62:63], v[46:47], v[24:25] op_sel_hi:[1,0,1]
	ds_read2st64_b32 v[112:113], v65 offset0:64 offset1:65
	ds_read2st64_b32 v[114:115], v65 offset0:66 offset1:67
	ds_read2st64_b32 v[116:117], v65 offset0:68 offset1:69
	ds_read2st64_b32 v[46:47], v65 offset0:70 offset1:71
	s_waitcnt lgkmcnt(11)
	v_pk_fma_f32 v[76:77], v[60:61], v[100:101], v[76:77] op_sel_hi:[1,0,1]
	s_waitcnt lgkmcnt(3)
	v_pk_fma_f32 v[118:119], v[62:63], v[112:113], v[44:45] op_sel_hi:[1,0,1]
	ds_read2st64_b32 v[120:121], v65 offset0:96 offset1:97
	ds_read2st64_b32 v[122:123], v65 offset0:98 offset1:99
	ds_read2st64_b32 v[124:125], v65 offset0:100 offset1:101
	ds_read2st64_b32 v[44:45], v65 offset0:102 offset1:103
	ds_read2st64_b32 v[128:129], v65 offset0:128 offset1:129
	ds_read2st64_b32 v[130:131], v65 offset0:130 offset1:131
	ds_read2st64_b32 v[132:133], v65 offset0:132 offset1:133
	ds_read2st64_b32 v[24:25], v65 offset0:134 offset1:135
	ds_read2st64_b32 v[134:135], v65 offset0:160 offset1:161
	ds_read2st64_b32 v[136:137], v65 offset0:162 offset1:163
	ds_read2st64_b32 v[138:139], v65 offset0:164 offset1:165
	ds_read2st64_b32 v[26:27], v65 offset0:166 offset1:167
	s_waitcnt lgkmcnt(11)
	v_pk_fma_f32 v[126:127], v[62:63], v[120:121], v[54:55] op_sel_hi:[1,0,1]
	s_waitcnt lgkmcnt(3)
	v_pk_fma_f32 v[140:141], v[62:63], v[134:135], v[28:29] op_sel_hi:[1,0,1]
	ds_read2st64_b32 v[142:143], v65 offset0:192 offset1:193
	ds_read2st64_b32 v[144:145], v65 offset0:194 offset1:195
	ds_read2st64_b32 v[146:147], v65 offset0:196 offset1:197
	ds_read2st64_b32 v[28:29], v65 offset0:198 offset1:199
	v_pk_fma_f32 v[72:73], v[62:63], v[100:101], v[72:73] op_sel_hi:[1,0,1]
	s_waitcnt lgkmcnt(3)
	v_pk_fma_f32 v[148:149], v[62:63], v[142:143], v[30:31] op_sel_hi:[1,0,1]
	ds_read2st64_b32 v[150:151], v65 offset0:224 offset1:225
	ds_read2st64_b32 v[152:153], v65 offset0:226 offset1:227
	ds_read2st64_b32 v[54:55], v65 offset0:228 offset1:229
	ds_read2st64_b32 v[30:31], v65 offset0:230 offset1:231
	v_pk_fma_f32 v[68:69], v[60:61], v[106:107], v[68:69] op_sel_hi:[1,0,1]
	v_pk_fma_f32 v[58:59], v[60:61], v[112:113], v[58:59] op_sel_hi:[1,0,1]
	v_pk_fma_f32 v[56:57], v[60:61], v[120:121], v[56:57] op_sel_hi:[1,0,1]
	v_pk_fma_f32 v[42:43], v[60:61], v[128:129], v[42:43] op_sel_hi:[1,0,1]
	v_pk_fma_f32 v[38:39], v[60:61], v[134:135], v[38:39] op_sel_hi:[1,0,1]
	v_pk_fma_f32 v[36:37], v[60:61], v[142:143], v[36:37] op_sel_hi:[1,0,1]
	s_waitcnt lgkmcnt(3)
	v_pk_fma_f32 v[34:35], v[60:61], v[150:151], v[34:35] op_sel_hi:[1,0,1]
	v_mov_b32_e32 v60, v101
	v_pk_fma_f32 v[66:67], v[62:63], v[106:107], v[66:67] op_sel_hi:[1,0,1]
	v_pk_fma_f32 v[40:41], v[62:63], v[128:129], v[40:41] op_sel_hi:[1,0,1]
	v_pk_fma_f32 v[32:33], v[62:63], v[150:151], v[32:33] op_sel_hi:[1,0,1]
	s_waitcnt vmcnt(6)
	v_pk_fma_f32 v[62:63], v[78:79], v[60:61], v[76:77] op_sel_hi:[1,0,1]
	v_pk_fma_f32 v[60:61], v[80:81], v[60:61], v[72:73] op_sel_hi:[1,0,1]
	v_mov_b32_e32 v72, v107
	v_mov_b32_e32 v100, v129
	v_pk_fma_f32 v[68:69], v[78:79], v[72:73], v[68:69] op_sel_hi:[1,0,1]
	v_pk_fma_f32 v[66:67], v[80:81], v[72:73], v[66:67] op_sel_hi:[1,0,1]
	v_mov_b32_e32 v72, v113
	v_mov_b32_e32 v76, v121
	v_pk_fma_f32 v[42:43], v[78:79], v[100:101], v[42:43] op_sel_hi:[1,0,1]
	v_pk_fma_f32 v[40:41], v[80:81], v[100:101], v[40:41] op_sel_hi:[1,0,1]
	v_mov_b32_e32 v100, v135
	v_mov_b32_e32 v106, v143
	v_mov_b32_e32 v112, v151
	v_pk_fma_f32 v[58:59], v[78:79], v[72:73], v[58:59] op_sel_hi:[1,0,1]
	v_pk_fma_f32 v[56:57], v[78:79], v[76:77], v[56:57] op_sel_hi:[1,0,1]
	v_pk_fma_f32 v[38:39], v[78:79], v[100:101], v[38:39] op_sel_hi:[1,0,1]
	v_pk_fma_f32 v[36:37], v[78:79], v[106:107], v[36:37] op_sel_hi:[1,0,1]
	v_pk_fma_f32 v[34:35], v[78:79], v[112:113], v[34:35] op_sel_hi:[1,0,1]
	v_pk_fma_f32 v[78:79], v[78:79], v[64:65], v[96:97] op_sel_hi:[1,0,1]
	s_waitcnt vmcnt(5)
	v_pk_fma_f32 v[62:63], v[82:83], v[102:103], v[62:63] op_sel_hi:[1,0,1]
	v_pk_fma_f32 v[78:79], v[82:83], v[70:71], v[78:79] op_sel_hi:[1,0,1]
	v_pk_fma_f32 v[60:61], v[84:85], v[102:103], v[60:61] op_sel_hi:[1,0,1]
	v_pk_fma_f32 v[68:69], v[82:83], v[108:109], v[68:69] op_sel_hi:[1,0,1]
	v_pk_fma_f32 v[58:59], v[82:83], v[114:115], v[58:59] op_sel_hi:[1,0,1]
	v_pk_fma_f32 v[56:57], v[82:83], v[122:123], v[56:57] op_sel_hi:[1,0,1]
	v_pk_fma_f32 v[42:43], v[82:83], v[130:131], v[42:43] op_sel_hi:[1,0,1]
	v_pk_fma_f32 v[38:39], v[82:83], v[136:137], v[38:39] op_sel_hi:[1,0,1]
	v_pk_fma_f32 v[36:37], v[82:83], v[144:145], v[36:37] op_sel_hi:[1,0,1]
	s_waitcnt lgkmcnt(2)
	v_pk_fma_f32 v[34:35], v[82:83], v[152:153], v[34:35] op_sel_hi:[1,0,1]
	v_mov_b32_e32 v82, v103
	v_pk_fma_f32 v[72:73], v[80:81], v[72:73], v[118:119] op_sel_hi:[1,0,1]
	v_pk_fma_f32 v[64:65], v[80:81], v[64:65], v[98:99] op_sel_hi:[1,0,1]
	v_pk_fma_f32 v[66:67], v[84:85], v[108:109], v[66:67] op_sel_hi:[1,0,1]
	s_waitcnt vmcnt(4)
	v_pk_fma_f32 v[62:63], v[86:87], v[82:83], v[62:63] op_sel_hi:[1,0,1]
	v_pk_fma_f32 v[60:61], v[88:89], v[82:83], v[60:61] op_sel_hi:[1,0,1]
	v_mov_b32_e32 v82, v109
	v_pk_fma_f32 v[76:77], v[80:81], v[76:77], v[126:127] op_sel_hi:[1,0,1]
	v_pk_fma_f32 v[64:65], v[84:85], v[70:71], v[64:65] op_sel_hi:[1,0,1]
	v_pk_fma_f32 v[70:71], v[84:85], v[114:115], v[72:73] op_sel_hi:[1,0,1]
	v_pk_fma_f32 v[68:69], v[86:87], v[82:83], v[68:69] op_sel_hi:[1,0,1]
	v_pk_fma_f32 v[82:83], v[88:89], v[82:83], v[66:67] op_sel_hi:[1,0,1]
	v_mov_b32_e32 v66, v115
	v_pk_fma_f32 v[72:73], v[84:85], v[122:123], v[76:77] op_sel_hi:[1,0,1]
	v_pk_fma_f32 v[58:59], v[86:87], v[66:67], v[58:59] op_sel_hi:[1,0,1]
	v_pk_fma_f32 v[70:71], v[88:89], v[66:67], v[70:71] op_sel_hi:[1,0,1]
	v_mov_b32_e32 v66, v123
	v_pk_fma_f32 v[100:101], v[80:81], v[100:101], v[140:141] op_sel_hi:[1,0,1]
	v_pk_fma_f32 v[40:41], v[84:85], v[130:131], v[40:41] op_sel_hi:[1,0,1]
	v_pk_fma_f32 v[56:57], v[86:87], v[66:67], v[56:57] op_sel_hi:[1,0,1]
	v_pk_fma_f32 v[72:73], v[88:89], v[66:67], v[72:73] op_sel_hi:[1,0,1]
	v_mov_b32_e32 v66, v131
	v_pk_fma_f32 v[106:107], v[80:81], v[106:107], v[148:149] op_sel_hi:[1,0,1]
	v_pk_fma_f32 v[76:77], v[84:85], v[136:137], v[100:101] op_sel_hi:[1,0,1]
	v_pk_fma_f32 v[42:43], v[86:87], v[66:67], v[42:43] op_sel_hi:[1,0,1]
	v_pk_fma_f32 v[40:41], v[88:89], v[66:67], v[40:41] op_sel_hi:[1,0,1]
	v_mov_b32_e32 v66, v137
	v_pk_fma_f32 v[32:33], v[80:81], v[112:113], v[32:33] op_sel_hi:[1,0,1]
	v_pk_fma_f32 v[80:81], v[84:85], v[144:145], v[106:107] op_sel_hi:[1,0,1]
	v_pk_fma_f32 v[38:39], v[86:87], v[66:67], v[38:39] op_sel_hi:[1,0,1]
	v_pk_fma_f32 v[76:77], v[88:89], v[66:67], v[76:77] op_sel_hi:[1,0,1]
	v_mov_b32_e32 v66, v145
	v_pk_fma_f32 v[32:33], v[84:85], v[152:153], v[32:33] op_sel_hi:[1,0,1]
	v_pk_fma_f32 v[36:37], v[86:87], v[66:67], v[36:37] op_sel_hi:[1,0,1]
	v_pk_fma_f32 v[80:81], v[88:89], v[66:67], v[80:81] op_sel_hi:[1,0,1]
	v_mov_b32_e32 v66, v153
	v_pk_fma_f32 v[32:33], v[88:89], v[66:67], v[32:33] op_sel_hi:[1,0,1]
	v_pk_fma_f32 v[34:35], v[86:87], v[66:67], v[34:35] op_sel_hi:[1,0,1]
	v_pk_fma_f32 v[66:67], v[86:87], v[74:75], v[78:79] op_sel_hi:[1,0,1]
	v_pk_fma_f32 v[74:75], v[88:89], v[74:75], v[64:65] op_sel_hi:[1,0,1]
	s_waitcnt vmcnt(3)
	v_pk_fma_f32 v[62:63], v[90:91], v[104:105], v[62:63] op_sel_hi:[1,0,1]
	v_pk_fma_f32 v[60:61], v[92:93], v[104:105], v[60:61] op_sel_hi:[1,0,1]
	s_waitcnt lgkmcnt(1)
	v_pk_fma_f32 v[78:79], v[92:93], v[54:55], v[32:33] op_sel_hi:[1,0,1]
	v_mov_b32_e32 v32, v105
	v_pk_fma_f32 v[64:65], v[90:91], v[94:95], v[66:67] op_sel_hi:[1,0,1]
	v_pk_fma_f32 v[66:67], v[92:93], v[94:95], v[74:75] op_sel_hi:[1,0,1]
	v_pk_fma_f32 v[68:69], v[90:91], v[110:111], v[68:69] op_sel_hi:[1,0,1]
	v_pk_fma_f32 v[82:83], v[92:93], v[110:111], v[82:83] op_sel_hi:[1,0,1]
	v_pk_fma_f32 v[86:87], v[92:93], v[124:125], v[72:73] op_sel_hi:[1,0,1]
	s_waitcnt vmcnt(2)
	v_pk_fma_f32 v[72:73], v[10:11], v[32:33], v[62:63] op_sel_hi:[1,0,1]
	v_pk_fma_f32 v[74:75], v[12:13], v[32:33], v[60:61] op_sel_hi:[1,0,1]
	v_mov_b32_e32 v32, v111
	v_pk_fma_f32 v[58:59], v[90:91], v[116:117], v[58:59] op_sel_hi:[1,0,1]
	v_pk_fma_f32 v[84:85], v[92:93], v[116:117], v[70:71] op_sel_hi:[1,0,1]
	v_pk_fma_f32 v[68:69], v[10:11], v[32:33], v[68:69] op_sel_hi:[1,0,1]
	v_pk_fma_f32 v[70:71], v[12:13], v[32:33], v[82:83] op_sel_hi:[1,0,1]
	v_mov_b32_e32 v32, v117
	v_pk_fma_f32 v[56:57], v[90:91], v[124:125], v[56:57] op_sel_hi:[1,0,1]
	v_pk_fma_f32 v[42:43], v[90:91], v[132:133], v[42:43] op_sel_hi:[1,0,1]
	v_pk_fma_f32 v[40:41], v[92:93], v[132:133], v[40:41] op_sel_hi:[1,0,1]
	v_pk_fma_f32 v[88:89], v[92:93], v[138:139], v[76:77] op_sel_hi:[1,0,1]
	v_pk_fma_f32 v[76:77], v[90:91], v[54:55], v[34:35] op_sel_hi:[1,0,1]
	v_pk_fma_f32 v[60:61], v[10:11], v[32:33], v[58:59] op_sel_hi:[1,0,1]
	v_pk_fma_f32 v[62:63], v[12:13], v[32:33], v[84:85] op_sel_hi:[1,0,1]
	v_mov_b32_e32 v32, v125
	v_mov_b32_e32 v34, v133
	v_pk_fma_f32 v[38:39], v[90:91], v[138:139], v[38:39] op_sel_hi:[1,0,1]
	v_pk_fma_f32 v[94:95], v[90:91], v[146:147], v[36:37] op_sel_hi:[1,0,1]
	v_pk_fma_f32 v[80:81], v[92:93], v[146:147], v[80:81] op_sel_hi:[1,0,1]
	v_pk_fma_f32 v[56:57], v[10:11], v[32:33], v[56:57] op_sel_hi:[1,0,1]
	v_pk_fma_f32 v[58:59], v[12:13], v[32:33], v[86:87] op_sel_hi:[1,0,1]
	v_pk_fma_f32 v[32:33], v[10:11], v[34:35], v[42:43] op_sel_hi:[1,0,1]
	v_pk_fma_f32 v[34:35], v[12:13], v[34:35], v[40:41] op_sel_hi:[1,0,1]
	v_mov_b32_e32 v40, v139
	v_mov_b32_e32 v42, v147
	v_pk_fma_f32 v[36:37], v[10:11], v[40:41], v[38:39] op_sel_hi:[1,0,1]
	v_pk_fma_f32 v[38:39], v[12:13], v[40:41], v[88:89] op_sel_hi:[1,0,1]
	v_pk_fma_f32 v[40:41], v[10:11], v[42:43], v[94:95] op_sel_hi:[1,0,1]
	v_pk_fma_f32 v[42:43], v[12:13], v[42:43], v[80:81] op_sel_hi:[1,0,1]
	v_mov_b32_e32 v80, v55
	v_pk_fma_f32 v[54:55], v[10:11], v[80:81], v[76:77] op_sel_hi:[1,0,1]
	v_pk_fma_f32 v[76:77], v[12:13], v[80:81], v[78:79] op_sel_hi:[1,0,1]
	v_pk_fma_f32 v[10:11], v[10:11], v[52:53], v[64:65] op_sel_hi:[1,0,1]
	v_pk_fma_f32 v[12:13], v[12:13], v[52:53], v[66:67] op_sel_hi:[1,0,1]
	v_mov_b32_e32 v78, v51
	v_mov_b32_e32 v66, v49
	v_mov_b32_e32 v64, v47
	v_mov_b32_e32 v52, v45
	s_waitcnt vmcnt(1)
	v_pk_fma_f32 v[72:73], v[6:7], v[50:51], v[72:73] op_sel_hi:[1,0,1]
	v_pk_fma_f32 v[74:75], v[8:9], v[50:51], v[74:75] op_sel_hi:[1,0,1]
	v_mov_b32_e32 v50, v25
	v_pk_fma_f32 v[68:69], v[6:7], v[48:49], v[68:69] op_sel_hi:[1,0,1]
	v_pk_fma_f32 v[70:71], v[8:9], v[48:49], v[70:71] op_sel_hi:[1,0,1]
	v_mov_b32_e32 v48, v27
	v_pk_fma_f32 v[60:61], v[6:7], v[46:47], v[60:61] op_sel_hi:[1,0,1]
	v_pk_fma_f32 v[62:63], v[8:9], v[46:47], v[62:63] op_sel_hi:[1,0,1]
	v_mov_b32_e32 v46, v29
	v_pk_fma_f32 v[56:57], v[6:7], v[44:45], v[56:57] op_sel_hi:[1,0,1]
	v_pk_fma_f32 v[82:83], v[8:9], v[44:45], v[58:59] op_sel_hi:[1,0,1]
	s_waitcnt lgkmcnt(0)
	v_mov_b32_e32 v80, v31
	v_pk_fma_f32 v[32:33], v[6:7], v[24:25], v[32:33] op_sel_hi:[1,0,1]
	v_pk_fma_f32 v[24:25], v[8:9], v[24:25], v[34:35] op_sel_hi:[1,0,1]
	v_pk_fma_f32 v[34:35], v[6:7], v[26:27], v[36:37] op_sel_hi:[1,0,1]
	v_pk_fma_f32 v[26:27], v[8:9], v[26:27], v[38:39] op_sel_hi:[1,0,1]
	v_pk_fma_f32 v[36:37], v[6:7], v[28:29], v[40:41] op_sel_hi:[1,0,1]
	v_pk_fma_f32 v[84:85], v[8:9], v[28:29], v[42:43] op_sel_hi:[1,0,1]
	v_pk_fma_f32 v[86:87], v[6:7], v[30:31], v[54:55] op_sel_hi:[1,0,1]
	v_pk_fma_f32 v[88:89], v[8:9], v[30:31], v[76:77] op_sel_hi:[1,0,1]
	v_pk_fma_f32 v[6:7], v[6:7], v[22:23], v[10:11] op_sel_hi:[1,0,1]
	v_pk_fma_f32 v[8:9], v[8:9], v[22:23], v[12:13] op_sel_hi:[1,0,1]
	s_waitcnt vmcnt(0)
	v_pk_fma_f32 v[76:77], v[2:3], v[78:79], v[72:73] op_sel_hi:[1,0,1]
	v_pk_fma_f32 v[72:73], v[4:5], v[78:79], v[74:75] op_sel_hi:[1,0,1]
	v_pk_fma_f32 v[68:69], v[2:3], v[66:67], v[68:69] op_sel_hi:[1,0,1]
	v_pk_fma_f32 v[66:67], v[4:5], v[66:67], v[70:71] op_sel_hi:[1,0,1]
	v_pk_fma_f32 v[58:59], v[2:3], v[64:65], v[60:61] op_sel_hi:[1,0,1]
	v_pk_fma_f32 v[44:45], v[4:5], v[64:65], v[62:63] op_sel_hi:[1,0,1]
	v_pk_fma_f32 v[56:57], v[2:3], v[52:53], v[56:57] op_sel_hi:[1,0,1]
	v_pk_fma_f32 v[54:55], v[4:5], v[52:53], v[82:83] op_sel_hi:[1,0,1]
	v_pk_fma_f32 v[42:43], v[2:3], v[50:51], v[32:33] op_sel_hi:[1,0,1]
	v_pk_fma_f32 v[40:41], v[4:5], v[50:51], v[24:25] op_sel_hi:[1,0,1]
	v_pk_fma_f32 v[38:39], v[2:3], v[48:49], v[34:35] op_sel_hi:[1,0,1]
	v_pk_fma_f32 v[28:29], v[4:5], v[48:49], v[26:27] op_sel_hi:[1,0,1]
	v_pk_fma_f32 v[36:37], v[2:3], v[46:47], v[36:37] op_sel_hi:[1,0,1]
	v_pk_fma_f32 v[30:31], v[4:5], v[46:47], v[84:85] op_sel_hi:[1,0,1]
	v_pk_fma_f32 v[34:35], v[2:3], v[80:81], v[86:87] op_sel_hi:[1,0,1]
	v_pk_fma_f32 v[32:33], v[4:5], v[80:81], v[88:89] op_sel_hi:[1,0,1]
	v_pk_fma_f32 v[26:27], v[2:3], v[0:1], v[6:7] op_sel_hi:[1,0,1]
	v_pk_fma_f32 v[24:25], v[4:5], v[0:1], v[8:9] op_sel_hi:[1,0,1]
	s_cbranch_scc0 .LBB0_417
	v_and_b32_e32 v2, 64, v226
	v_xor_b32_e32 v0, 8, v226
	v_add_u32_e32 v3, 64, v2
	v_cmp_lt_i32_e64 s[42:43], v0, v3
	v_xor_b32_e32 v2, 16, v226
	v_xor_b32_e32 v6, 32, v226
	v_cndmask_b32_e64 v0, v226, v0, s[42:43]
	v_lshlrev_b32_e32 v0, 2, v0
	v_cmp_lt_i32_e64 s[42:43], v2, v3
	s_nop 1
	v_cndmask_b32_e64 v2, v226, v2, s[42:43]
	v_lshlrev_b32_e32 v2, 2, v2
	v_cmp_lt_i32_e64 s[42:43], v6, v3
	s_nop 1
	v_cndmask_b32_e64 v3, v226, v6, s[42:43]
	v_lshlrev_b32_e32 v3, 2, v3
	ds_bpermute_b32 v78, v0, v76
	ds_bpermute_b32 v79, v0, v77
	ds_bpermute_b32 v80, v0, v72
	ds_bpermute_b32 v81, v0, v73
	ds_bpermute_b32 v82, v0, v68
	ds_bpermute_b32 v83, v0, v69
	ds_bpermute_b32 v84, v0, v66
	ds_bpermute_b32 v85, v0, v67
	ds_bpermute_b32 v86, v0, v58
	ds_bpermute_b32 v87, v0, v59
	ds_bpermute_b32 v88, v0, v44
	ds_bpermute_b32 v89, v0, v45
	s_waitcnt lgkmcnt(0)
	v_add_f32_e32 v76, v76, v78
	v_add_f32_e32 v77, v77, v79
	v_add_f32_e32 v72, v72, v80
	v_add_f32_e32 v73, v73, v81
	v_add_f32_e32 v68, v68, v82
	v_add_f32_e32 v69, v69, v83
	v_add_f32_e32 v66, v66, v84
	v_add_f32_e32 v67, v67, v85
	v_add_f32_e32 v58, v58, v86
	v_add_f32_e32 v59, v59, v87
	v_add_f32_e32 v44, v44, v88
	v_add_f32_e32 v45, v45, v89
	ds_bpermute_b32 v78, v2, v76
	ds_bpermute_b32 v79, v2, v77
	ds_bpermute_b32 v80, v2, v72
	ds_bpermute_b32 v81, v2, v73
	ds_bpermute_b32 v82, v2, v68
	ds_bpermute_b32 v83, v2, v69
	ds_bpermute_b32 v84, v2, v66
	ds_bpermute_b32 v85, v2, v67
	ds_bpermute_b32 v86, v2, v58
	ds_bpermute_b32 v87, v2, v59
	ds_bpermute_b32 v88, v2, v44
	ds_bpermute_b32 v89, v2, v45
	s_waitcnt lgkmcnt(0)
	v_add_f32_e32 v76, v76, v78
	v_add_f32_e32 v77, v77, v79
	v_add_f32_e32 v72, v72, v80
	v_add_f32_e32 v73, v73, v81
	v_add_f32_e32 v68, v68, v82
	v_add_f32_e32 v69, v69, v83
	v_add_f32_e32 v66, v66, v84
	v_add_f32_e32 v67, v67, v85
	v_add_f32_e32 v58, v58, v86
	v_add_f32_e32 v59, v59, v87
	v_add_f32_e32 v44, v44, v88
	v_add_f32_e32 v45, v45, v89
	ds_bpermute_b32 v78, v3, v76
	ds_bpermute_b32 v79, v3, v77
	ds_bpermute_b32 v80, v3, v72
	ds_bpermute_b32 v81, v3, v73
	ds_bpermute_b32 v82, v3, v68
	ds_bpermute_b32 v83, v3, v69
	ds_bpermute_b32 v84, v3, v66
	ds_bpermute_b32 v85, v3, v67
	ds_bpermute_b32 v86, v3, v58
	ds_bpermute_b32 v87, v3, v59
	ds_bpermute_b32 v88, v3, v44
	ds_bpermute_b32 v89, v3, v45
	s_waitcnt lgkmcnt(0)
	v_add_f32_e32 v76, v76, v78
	v_add_f32_e32 v77, v77, v79
	v_add_f32_e32 v72, v72, v80
	v_add_f32_e32 v73, v73, v81
	v_add_f32_e32 v68, v68, v82
	v_add_f32_e32 v69, v69, v83
	v_add_f32_e32 v66, v66, v84
	v_add_f32_e32 v67, v67, v85
	v_add_f32_e32 v58, v58, v86
	v_add_f32_e32 v59, v59, v87
	v_add_f32_e32 v44, v44, v88
	v_add_f32_e32 v45, v45, v89
	s_and_saveexec_b64 s[4:5], vcc
	ds_write_b32 v53, v76
	ds_write_b32 v53, v77 offset:4
	ds_write_b32 v53, v72 offset:8
	ds_write_b32 v53, v73 offset:12
	ds_write_b32 v53, v68 offset:128
	ds_write_b32 v53, v69 offset:132
	ds_write_b32 v53, v66 offset:136
	ds_write_b32 v53, v67 offset:140
	ds_write_b32 v53, v58 offset:256
	ds_write_b32 v53, v59 offset:260
	ds_write_b32 v53, v44 offset:264
	ds_write_b32 v53, v45 offset:268
	s_or_b64 exec, exec, s[4:5]
	ds_bpermute_b32 v78, v0, v56
	ds_bpermute_b32 v79, v0, v57
	ds_bpermute_b32 v80, v0, v54
	ds_bpermute_b32 v81, v0, v55
	ds_bpermute_b32 v82, v0, v42
	ds_bpermute_b32 v83, v0, v43
	ds_bpermute_b32 v84, v0, v40
	ds_bpermute_b32 v85, v0, v41
	ds_bpermute_b32 v86, v0, v38
	ds_bpermute_b32 v87, v0, v39
	ds_bpermute_b32 v88, v0, v28
	ds_bpermute_b32 v89, v0, v29
	s_waitcnt lgkmcnt(0)
	v_add_f32_e32 v56, v56, v78
	v_add_f32_e32 v57, v57, v79
	v_add_f32_e32 v54, v54, v80
	v_add_f32_e32 v55, v55, v81
	v_add_f32_e32 v42, v42, v82
	v_add_f32_e32 v43, v43, v83
	v_add_f32_e32 v40, v40, v84
	v_add_f32_e32 v41, v41, v85
	v_add_f32_e32 v38, v38, v86
	v_add_f32_e32 v39, v39, v87
	v_add_f32_e32 v28, v28, v88
	v_add_f32_e32 v29, v29, v89
	ds_bpermute_b32 v78, v2, v56
	ds_bpermute_b32 v79, v2, v57
	ds_bpermute_b32 v80, v2, v54
	ds_bpermute_b32 v81, v2, v55
	ds_bpermute_b32 v82, v2, v42
	ds_bpermute_b32 v83, v2, v43
	ds_bpermute_b32 v84, v2, v40
	ds_bpermute_b32 v85, v2, v41
	ds_bpermute_b32 v86, v2, v38
	ds_bpermute_b32 v87, v2, v39
	ds_bpermute_b32 v88, v2, v28
	ds_bpermute_b32 v89, v2, v29
	s_waitcnt lgkmcnt(0)
	v_add_f32_e32 v56, v56, v78
	v_add_f32_e32 v57, v57, v79
	v_add_f32_e32 v54, v54, v80
	v_add_f32_e32 v55, v55, v81
	v_add_f32_e32 v42, v42, v82
	v_add_f32_e32 v43, v43, v83
	v_add_f32_e32 v40, v40, v84
	v_add_f32_e32 v41, v41, v85
	v_add_f32_e32 v38, v38, v86
	v_add_f32_e32 v39, v39, v87
	v_add_f32_e32 v28, v28, v88
	v_add_f32_e32 v29, v29, v89
	ds_bpermute_b32 v78, v3, v56
	ds_bpermute_b32 v79, v3, v57
	ds_bpermute_b32 v80, v3, v54
	ds_bpermute_b32 v81, v3, v55
	ds_bpermute_b32 v82, v3, v42
	ds_bpermute_b32 v83, v3, v43
	ds_bpermute_b32 v84, v3, v40
	ds_bpermute_b32 v85, v3, v41
	ds_bpermute_b32 v86, v3, v38
	ds_bpermute_b32 v87, v3, v39
	ds_bpermute_b32 v88, v3, v28
	ds_bpermute_b32 v89, v3, v29
	s_waitcnt lgkmcnt(0)
	v_add_f32_e32 v56, v56, v78
	v_add_f32_e32 v57, v57, v79
	v_add_f32_e32 v54, v54, v80
	v_add_f32_e32 v55, v55, v81
	v_add_f32_e32 v42, v42, v82
	v_add_f32_e32 v43, v43, v83
	v_add_f32_e32 v40, v40, v84
	v_add_f32_e32 v41, v41, v85
	v_add_f32_e32 v38, v38, v86
	v_add_f32_e32 v39, v39, v87
	v_add_f32_e32 v28, v28, v88
	v_add_f32_e32 v29, v29, v89
	s_and_saveexec_b64 s[4:5], vcc
	ds_write_b32 v53, v56 offset:384
	ds_write_b32 v53, v57 offset:388
	ds_write_b32 v53, v54 offset:392
	ds_write_b32 v53, v55 offset:396
	ds_write_b32 v53, v42 offset:512
	ds_write_b32 v53, v43 offset:516
	ds_write_b32 v53, v40 offset:520
	ds_write_b32 v53, v41 offset:524
	ds_write_b32 v53, v38 offset:640
	ds_write_b32 v53, v39 offset:644
	ds_write_b32 v53, v28 offset:648
	ds_write_b32 v53, v29 offset:652
	s_or_b64 exec, exec, s[4:5]
	ds_bpermute_b32 v78, v0, v36
	ds_bpermute_b32 v79, v0, v37
	ds_bpermute_b32 v80, v0, v30
	ds_bpermute_b32 v81, v0, v31
	ds_bpermute_b32 v82, v0, v34
	ds_bpermute_b32 v83, v0, v35
	ds_bpermute_b32 v84, v0, v32
	ds_bpermute_b32 v85, v0, v33
	ds_bpermute_b32 v86, v0, v26
	ds_bpermute_b32 v87, v0, v27
	ds_bpermute_b32 v88, v0, v24
	ds_bpermute_b32 v89, v0, v25
	s_waitcnt lgkmcnt(0)
	v_add_f32_e32 v36, v36, v78
	v_add_f32_e32 v37, v37, v79
	v_add_f32_e32 v30, v30, v80
	v_add_f32_e32 v31, v31, v81
	v_add_f32_e32 v34, v34, v82
	v_add_f32_e32 v35, v35, v83
	v_add_f32_e32 v32, v32, v84
	v_add_f32_e32 v33, v33, v85
	v_add_f32_e32 v26, v26, v86
	v_add_f32_e32 v27, v27, v87
	v_add_f32_e32 v24, v24, v88
	v_add_f32_e32 v25, v25, v89
	ds_bpermute_b32 v78, v2, v36
	ds_bpermute_b32 v79, v2, v37
	ds_bpermute_b32 v80, v2, v30
	ds_bpermute_b32 v81, v2, v31
	ds_bpermute_b32 v82, v2, v34
	ds_bpermute_b32 v83, v2, v35
	ds_bpermute_b32 v84, v2, v32
	ds_bpermute_b32 v85, v2, v33
	ds_bpermute_b32 v86, v2, v26
	ds_bpermute_b32 v87, v2, v27
	ds_bpermute_b32 v88, v2, v24
	ds_bpermute_b32 v89, v2, v25
	s_waitcnt lgkmcnt(0)
	v_add_f32_e32 v36, v36, v78
	v_add_f32_e32 v37, v37, v79
	v_add_f32_e32 v30, v30, v80
	v_add_f32_e32 v31, v31, v81
	v_add_f32_e32 v34, v34, v82
	v_add_f32_e32 v35, v35, v83
	v_add_f32_e32 v32, v32, v84
	v_add_f32_e32 v33, v33, v85
	v_add_f32_e32 v26, v26, v86
	v_add_f32_e32 v27, v27, v87
	v_add_f32_e32 v24, v24, v88
	v_add_f32_e32 v25, v25, v89
	ds_bpermute_b32 v78, v3, v36
	ds_bpermute_b32 v79, v3, v37
	ds_bpermute_b32 v80, v3, v30
	ds_bpermute_b32 v81, v3, v31
	ds_bpermute_b32 v82, v3, v34
	ds_bpermute_b32 v83, v3, v35
	ds_bpermute_b32 v84, v3, v32
	ds_bpermute_b32 v85, v3, v33
	ds_bpermute_b32 v86, v3, v26
	ds_bpermute_b32 v87, v3, v27
	ds_bpermute_b32 v88, v3, v24
	ds_bpermute_b32 v89, v3, v25
	s_waitcnt lgkmcnt(0)
	v_add_f32_e32 v36, v36, v78
	v_add_f32_e32 v37, v37, v79
	v_add_f32_e32 v30, v30, v80
	v_add_f32_e32 v31, v31, v81
	v_add_f32_e32 v34, v34, v82
	v_add_f32_e32 v35, v35, v83
	v_add_f32_e32 v32, v32, v84
	v_add_f32_e32 v33, v33, v85
	v_add_f32_e32 v26, v26, v86
	v_add_f32_e32 v27, v27, v87
	v_add_f32_e32 v24, v24, v88
	v_add_f32_e32 v25, v25, v89
	s_and_saveexec_b64 s[4:5], vcc
	ds_write_b32 v53, v36 offset:768
	ds_write_b32 v53, v37 offset:772
	ds_write_b32 v53, v30 offset:776
	ds_write_b32 v53, v31 offset:780
	ds_write_b32 v53, v34 offset:896
	ds_write_b32 v53, v35 offset:900
	ds_write_b32 v53, v32 offset:904
	ds_write_b32 v53, v33 offset:908
	ds_write_b32 v53, v26 offset:1024
	ds_write_b32 v53, v27 offset:1028
	ds_write_b32 v53, v24 offset:1032
	ds_write_b32 v53, v25 offset:1036
	s_or_b64 exec, exec, s[4:5]
.LBB0_490:
	s_or_b64 exec, exec, s[4:5]
	s_waitcnt lgkmcnt(0)
	s_barrier
	s_and_saveexec_b64 s[4:5], s[40:41]
	s_cbranch_execz .LBB0_415
	s_mul_i32 s8, s7, 0x3000
	s_add_i32 s8, s8, s28
	v_or_b32_e32 v2, s8, v16
	v_ashrrev_i32_e32 v3, 31, v2
	v_lshl_add_u64 v[2:3], v[2:3], 2, s[46:47]
	global_load_dword v86, v[2:3], off
	ds_read_b32 v0, v23
	ds_read_b32 v78, v23 offset:1152
	ds_read_b32 v79, v23 offset:2304
	ds_read_b32 v80, v23 offset:3456
	ds_read_b32 v81, v23 offset:4608
	ds_read_b32 v82, v23 offset:5760
	ds_read_b32 v83, v23 offset:6912
	ds_read_b32 v84, v23 offset:8064
	v_mov_b64_e32 v[4:5], s[24:25]
	s_waitcnt lgkmcnt(0)
	v_add_f32_e32 v0, 0, v0
	v_add_f32_e32 v0, v0, v78
	v_add_f32_e32 v0, v0, v79
	v_add_f32_e32 v0, v0, v80
	v_add_f32_e32 v0, v0, v81
	v_add_f32_e32 v0, v0, v82
	v_add_f32_e32 v0, v0, v83
	v_add_f32_e32 v0, v0, v84
	s_waitcnt vmcnt(0)
	v_add_f32_e32 v6, v0, v86
	v_mad_u64_u32 v[2:3], s[8:9], s7, 9, v[14:15]
	v_mad_i64_i32 v[2:3], s[8:9], v2, s59, v[4:5]
	v_lshl_add_u64 v[2:3], s[28:29], 2, v[2:3]
	v_lshlrev_b32_e32 v0, 2, v16
	v_lshl_add_u64 v[2:3], v[2:3], 0, v[0:1]
	global_store_dword v[2:3], v6, off
	s_branch .LBB0_415
